# tile-skip bound of the differential units 170 -> 162 (terms beyond it are still exactly zero in f32: argument below -154)
# speedup vs baseline: 1.0001x; 1.0001x over previous
.LBB0_443:
	s_lshr_b32 s2, s15, 6
	s_ashr_i32 s78, s15, 8
	s_add_i32 s2, s2, s78
	s_and_b32 s10, s2, 3
	s_mul_i32 s3, s78, 23
	s_not_b32 s2, s10
	s_add_i32 s3, s3, s15
	s_lshl_b32 s4, s2, 1
	s_lshl_b32 s2, s78, 5
	s_and_b32 s48, s3, 63
	s_ashr_i32 s3, s2, 31
	s_lshl_b32 s34, s48, 7
	s_lshl_b64 s[2:3], s[2:3], 2
	s_add_u32 s2, s1, s2
	s_addc_u32 s3, s6, s3
	s_lshl_b32 s5, s10, 4
	v_mov_b32_e32 v0, s5
	global_load_dwordx4 v[2:5], v0, s[2:3]
	global_load_dwordx4 v[6:9], v0, s[2:3] offset:64
	v_cvt_f32_i32_e32 v0, s4
	s_waitcnt vmcnt(1)
	v_mov_b32_e32 v10, v2
	s_waitcnt vmcnt(0)
	v_mov_b32_e32 v11, v6
	v_mov_b32_e32 v6, v3
	v_mov_b32_e32 v2, v4
	v_mov_b32_e32 v3, v8
	v_mov_b32_e32 v8, v5
	v_pk_add_f32 v[4:5], v[10:11], v[6:7]
	v_pk_add_f32 v[2:3], v[2:3], v[8:9]
	v_mul_f32_e32 v4, v4, v5
	v_mul_f32_e32 v2, v2, v3
	v_mul_f32_e32 v3, 0x4f800000, v4
	v_cmp_gt_f32_e32 vcc, s35, v4
	v_mul_f32_e32 v5, 0x4f800000, v2
	v_cmp_gt_f32_e64 s[2:3], s35, v2
	v_cndmask_b32_e32 v4, v4, v3, vcc
	v_sqrt_f32_e32 v6, v4
	v_cndmask_b32_e64 v2, v2, v5, s[2:3]
	v_sqrt_f32_e32 v5, v2
	v_exp_f32_e32 v3, v0
	v_add_u32_e32 v0, -1, v6
	v_fma_f32 v10, -v0, v6, v4
	v_add_u32_e32 v8, -1, v5
	v_add_u32_e32 v7, 1, v6
	v_fma_f32 v12, -v8, v5, v2
	v_cmp_ge_f32_e64 s[4:5], 0, v10
	v_add_u32_e32 v9, 1, v5
	v_fma_f32 v11, -v7, v6, v4
	v_cndmask_b32_e64 v0, v6, v0, s[4:5]
	v_cmp_ge_f32_e64 s[4:5], 0, v12
	v_fma_f32 v13, -v9, v5, v2
	s_nop 0
	v_cndmask_b32_e64 v5, v5, v8, s[4:5]
	v_cmp_lt_f32_e64 s[4:5], 0, v11
	s_nop 1
	v_cndmask_b32_e64 v0, v0, v7, s[4:5]
	v_cmp_lt_f32_e64 s[4:5], 0, v13
	v_mul_f32_e32 v6, 0x37800000, v0
	v_cndmask_b32_e32 v0, v0, v6, vcc
	v_cndmask_b32_e64 v5, v5, v9, s[4:5]
	v_mul_f32_e32 v7, 0x37800000, v5
	v_cmp_class_f32_e32 vcc, v4, v222
	v_cndmask_b32_e64 v5, v5, v7, s[2:3]
	s_nop 0
	v_cndmask_b32_e32 v0, v0, v4, vcc
	v_cmp_class_f32_e32 vcc, v2, v222
	s_nop 1
	v_cndmask_b32_e32 v2, v5, v2, vcc
	v_max3_f32 v0, v0, 0, v2
	v_mul_f32_e32 v2, 0x3f828f5c, v0
	v_cmp_gt_f32_e32 vcc, 0x42200000, v2
	s_cmp_lg_u64 vcc, 0
	s_cselect_b32 s98, 1, 0
	s_mov_b32 s99, 0
	v_pk_mul_f32 v[200:201], v[2:3], s[8:9]
	s_nop 0
	v_add_f32_e32 v0, 0x43220000, v200
	v_div_scale_f32 v2, s[2:3], v201, v201, v0
	v_rcp_f32_e32 v3, v2
	v_div_scale_f32 v4, vcc, v0, v201, v0
	s_mov_b32 s2, 0x46000000
	v_fma_f32 v5, -v2, v3, 1.0
	v_fmac_f32_e32 v3, v5, v3
	v_mul_f32_e32 v5, v4, v3
	v_fma_f32 v6, -v2, v5, v4
	v_fmac_f32_e32 v5, v6, v3
	v_fma_f32 v2, -v2, v5, v4
	v_div_fmas_f32 v2, v2, v3, v5
	v_div_fixup_f32 v0, v2, v201, v0
	v_cvt_i32_f32_e32 v2, v0
	v_cmp_gt_f32_e32 vcc, s2, v0
	v_readfirstlane_b32 s2, v2
	s_add_i32 s4, s2, 1
	s_and_b64 s[2:3], vcc, exec
	s_cselect_b32 s2, s4, 0x2000
	s_sub_i32 s3, s34, s2
	s_add_i32 s2, s2, s34
	s_addk_i32 s2, 0x7f
	s_max_i32 s3, s3, 0
	s_min_i32 s2, s2, 0x1fff
	s_lshr_b32 s33, s3, 6
	s_ashr_i32 s4, s2, 6
	s_sub_i32 s2, s4, s33
	s_bitcmp1_b32 s2, 0
	s_cselect_b64 s[2:3], -1, 0
	s_and_b64 vcc, exec, s[2:3]
	s_cbranch_vccnz .LBB0_449
	s_cmpk_gt_i32 s4, 0x7e
	s_mov_b64 s[2:3], -1
	s_cbranch_scc0 .LBB0_446
	s_add_i32 s5, s33, -1
	s_mov_b64 s[2:3], 0
